# grid barrier: acquire-side L1 invalidate issued at arrival (completes during the wait) instead of after the release
# speedup vs baseline: 1.0184x; 1.0089x over previous
.LBB0_1326:
	s_waitcnt lgkmcnt(0)
	s_nop 0
	v_readfirstlane_b32 s2, v4
	v_readfirstlane_b32 s3, v2
	v_readlane_b32 s4, v254, 1
	s_lshl_b32 s0, s0, 8
	s_add_u32 s10, s38, s0
	s_addc_u32 s11, s39, 0
	s_add_u32 s12, s10, 0x1400
	s_addc_u32 s13, s11, 0
	s_add_i32 s5, s4, 1
	v_writelane_b32 v254, s5, 1
	s_mul_i32 s6, s5, s2
	s_mul_i32 s7, s5, s3
	v_mov_b32_e32 v5, 0
	global_atomic_add v6, v5, v228, s[12:13] sc0
	buffer_inv sc1
	s_add_u32 s12, s10, 0x2400
	s_addc_u32 s13, s11, 0
	s_waitcnt vmcnt(1)
	v_readfirstlane_b32 s8, v6
	s_add_i32 s8, s8, 1
	s_cmp_eq_u32 s8, s6
	s_cbranch_scc1 .Lxb_leader
	s_mov_b32 s9, 0

.Lxb_acquire:
	s_waitcnt vmcnt(0)
	s_branch .LBB0_10
